# replace the single cooperative-groups grid.sync (512 serialized atomics) by block-0 publish + poll on the same sync word, setup->fold dependency carried by one extra XCD barrier
# speedup vs baseline: 1.0060x; 1.0002x over previous
; #define KARGP(z_) ((const P*)(const void*)((const __attribute__((address_space(4))) char*)__builtin_amdgcn_kernarg_segment_ptr() + (z_)))
; __global__ void __launch_bounds__(NTHR, 2) mega(P p) {
;     ...
;   if (blockIdx.x == 0) { unsigned* bw = (unsigned*)(p.ws + O_BAR); for (int i = threadIdx.x; i < 3456; i += NTHR) bw[i] = 0u; }
;   {
;     OPAQUE_Z; const P& q = *KARGP(zz);
;     ph_mod(q, smem);
;     ph_convert(q, smem);
;   }
;   grid.sync();
.LBB0_9:
	s_or_b64 exec, exec, s[8:9]
	s_waitcnt vmcnt(0)
	s_barrier
	v_cmp_eq_u32_e32 vcc, 0, v128
	s_and_saveexec_b64 s[4:5], vcc
	s_cbranch_execz .Lcgf_z
	buffer_wbl2 sc1
	s_waitcnt vmcnt(0)
	s_load_dwordx2 s[6:7], s[12:13], 0x58
	v_mov_b32_e32 v4, 0
	v_mov_b32_e32 v5, 1
	s_waitcnt lgkmcnt(0)
	global_atomic_add v4, v5, s[6:7] offset:32
	s_waitcnt vmcnt(0)
.Lcgf_z:
	s_or_b64 exec, exec, s[4:5]
.LBB0_10:
	s_mov_b32 s33, 0
	s_ashr_i32 s78, s33, 31
	s_add_u32 s0, s88, s33
	s_addc_u32 s1, s89, s78
	s_mov_b32 s24, 0
	s_load_dwordx2 s[14:15], s[0:1], 0x118
	v_add_u32_e32 v122, s24, v128
	s_movk_i32 s0, 0x2400
	v_cmp_gt_i32_e32 vcc, s0, v122
	s_and_saveexec_b64 s[10:11], vcc
	s_cbranch_execz .LBB0_22
	s_add_u32 s0, s88, s33
	s_addc_u32 s1, s89, s78
	s_load_dwordx2 s[18:19], s[0:1], 0x8
	s_load_dwordx2 s[16:17], s[0:1], 0x18
	v_max_i32_e32 v1, 0x2300, v122
	v_sub_u32_e32 v1, v1, v122
	s_movk_i32 s0, 0xff
	v_add_u32_e32 v1, 0xff, v1
	v_cmp_lt_u32_e32 vcc, s0, v1
	s_mov_b64 s[0:1], -1
	v_mov_b32_e32 v2, v122
	s_and_saveexec_b64 s[20:21], vcc
	s_cbranch_execz .LBB0_19
	v_lshrrev_b32_e32 v1, 8, v1
	v_add_u32_e32 v123, 0x100, v122
	v_add_u32_e32 v6, -1, v1
	v_cmp_lt_u32_e32 vcc, 1, v6
	v_mov_b32_e32 v4, 0
	v_mov_b64_e32 v[2:3], v[122:123]
	s_and_saveexec_b64 s[0:1], vcc
	s_cbranch_execz .LBB0_16
	v_lshrrev_b32_e32 v2, 1, v6
	v_add_u32_e32 v2, 1, v2
	v_and_b32_e32 v7, -2, v2
	v_lshlrev_b32_e32 v8, 2, v122
	s_mov_b32 s25, 0
	s_mov_b64 s[22:23], 0
	s_movk_i32 s26, 0x2000
	v_mov_b32_e32 v5, 0
	s_mov_b32 s27, 0xbfb8aa3b
	s_mov_b32 s28, 0x42ce8ed0
	s_mov_b32 s29, 0xc2b17218
	v_mov_b32_e32 v9, 0x7f800000
	v_mov_b64_e32 v[2:3], v[122:123]

; __global__ void __launch_bounds__(NTHR, 2) mega(P p) {
;     ...
;   grid.sync();
;   XcdBarrier xb = xcd_barrier_post((unsigned*)(p.ws + O_BAR));
.LBB0_624:
	s_or_b64 exec, exec, s[14:15]
	v_lshrrev_b32_e32 v2, 20, v0
	v_lshrrev_b32_e32 v0, 10, v0
	v_or_b32_e32 v0, v0, v2
	s_movk_i32 s0, 0x3ff
	v_and_or_b32 v0, v0, s0, v128
	v_cmp_eq_u32_e32 vcc, 0, v0
	s_waitcnt lgkmcnt(0)
	s_barrier
	s_and_saveexec_b64 s[0:1], vcc
	s_cbranch_execz .LBB0_634
	s_load_dwordx2 s[4:5], s[12:13], 0x58
	v_mov_b32_e32 v0, 0
	s_waitcnt lgkmcnt(0)
.Lcgf_poll:
	global_load_dword v3, v0, s[4:5] offset:32 sc1
	s_waitcnt vmcnt(0)
	v_and_b32_e32 v3, 0xffff, v3
	v_cmp_ne_u32_e32 vcc, 0, v3
	s_cbranch_vccnz .Lcgf_done
	s_sleep 1
	s_branch .Lcgf_poll

; __global__ void __launch_bounds__(NTHR, 2) mega(P p) {
;     ...
;   XcdBarrier xb = xcd_barrier_post((unsigned*)(p.ws + O_BAR));
; #pragma unroll 1
;   for (int st = -1; st < 40; st++) {
;     const int l = st < 0 ? 0 : st / 10;
;     const int ph = st < 0 ? -1 : st - l * 10;
;     const int need_ctx = l < 3;
;     const int nrows = need_ctx ? T_ALL : T_LAT;
;     switch (ph) {
.LBB0_637:
	s_or_b64 exec, exec, s[4:5]
	s_add_i32 s4, s90, s87
	s_add_u32 s6, s2, 0x2dd6da00
	s_addc_u32 s7, s3, 0
	v_writelane_b32 v253, s6, 2
	v_cvt_f32_u32_e32 v0, s90
	v_mov_b32_e32 v130, 0
	v_writelane_b32 v253, s7, 3
	s_add_u32 s6, s2, 0x2dd6dc00
	s_addc_u32 s7, s3, 0
	v_writelane_b32 v253, s6, 4
	v_rcp_iflag_f32_e32 v0, v0
	s_movk_i32 s48, 0x4000
	v_writelane_b32 v253, s7, 5
	s_add_u32 s6, s2, 0x2dd6dd00
	s_addc_u32 s7, s3, 0
	v_writelane_b32 v253, s6, 6
	v_mul_f32_e32 v0, 0x4f7ffffe, v0
	v_cvt_u32_f32_e32 v0, v0
	v_writelane_b32 v253, s7, 7
	s_add_u32 s6, s2, 0x2dd6de00
	s_addc_u32 s7, s3, 0
	v_writelane_b32 v253, s6, 8
	v_mov_b32_e32 v133, 0
	s_movk_i32 s49, 0x800
	v_writelane_b32 v253, s7, 9
	s_add_u32 s6, s2, 0x2dd6df00
	s_addc_u32 s7, s3, 0
	v_writelane_b32 v253, s6, 10
	s_movk_i32 s54, 0x100
	v_mov_b32_e32 v137, 0x3ba10414
	v_writelane_b32 v253, s7, 11
	s_add_u32 s6, s2, 0x2dd6e000
	s_addc_u32 s7, s3, 0
	v_writelane_b32 v253, s6, 12
	v_mov_b32_e32 v139, 0x3727c5ac
	v_mov_b32_e32 v210, 0x3ecc95a3
	v_writelane_b32 v253, s7, 13
	s_add_u32 s6, s2, 0x2dd6e100
	s_addc_u32 s7, s3, 0
	v_writelane_b32 v253, s6, 14
	v_mov_b32_e32 v211, 0x358637bd
	v_mbcnt_hi_u32_b32 v212, -1, v1
	v_writelane_b32 v253, s7, 15
	s_add_u32 s6, s2, 0x2dd6e200
	s_addc_u32 s7, s3, 0
	v_writelane_b32 v253, s6, 16
	v_mov_b32_e32 v213, 0xb9c68948
	v_mov_b32_e32 v214, 0x7f800000
	v_writelane_b32 v253, s7, 17
	s_add_u32 s6, s2, 0x2dd6e300
	s_addc_u32 s7, s3, 0
	v_writelane_b32 v253, s6, 18
	v_mov_b32_e32 v134, 0x3f317218
	v_mov_b32_e32 v216, 0x7fc00000
	v_writelane_b32 v253, s7, 19
	s_add_u32 s6, s2, 0x2dd6e400
	s_addc_u32 s7, s3, 0
	v_writelane_b32 v253, s6, 20
	v_mov_b32_e32 v217, 0xff800000
	v_mov_b32_e32 v126, 0x80
	v_writelane_b32 v253, s7, 21
	s_add_u32 s6, s2, 0x2dd6e500
	s_addc_u32 s7, s3, 0
	v_writelane_b32 v253, s6, 22
	v_mov_b32_e32 v246, 0x78
	v_mov_b32_e32 v251, 0x68
	v_writelane_b32 v253, s7, 23
	s_add_u32 s6, s2, 0x2dd6e600
	s_addc_u32 s7, s3, 0
	v_writelane_b32 v253, s6, 24
	v_mov_b32_e32 v222, 0xff
	v_mov_b32_e32 v223, 0x7ff
	v_writelane_b32 v253, s7, 25
	s_add_u32 s6, s2, 0x2dd6e700
	s_addc_u32 s7, s3, 0
	v_writelane_b32 v253, s6, 26
	v_mov_b32_e32 v252, 0x98
	v_mov_b32_e32 v226, 0xb0
	v_writelane_b32 v253, s7, 27
	s_add_u32 s6, s2, 0x2dd6e800
	s_addc_u32 s7, s3, 0
	v_writelane_b32 v253, s6, 28
	v_mov_b32_e32 v227, 0xa8
	v_mov_b32_e32 v228, 0x3e3504f3
	v_writelane_b32 v253, s7, 29
	s_add_u32 s6, s2, 0x2dd6e900
	s_addc_u32 s7, s3, 0
	v_writelane_b32 v253, s6, 30
	v_mov_b32_e32 v136, 0
	v_mov_b32_e32 v138, 0
	v_writelane_b32 v253, s7, 31
	s_add_u32 s6, s2, 0x2dd6ea00
	s_addc_u32 s7, s3, 0
	v_writelane_b32 v253, s6, 32
	s_mov_b32 s52, 0xbfb8aa3b
	s_movk_i32 s33, 0x90
	v_writelane_b32 v253, s7, 33
	s_add_u32 s6, s2, 0x2dd6eb00
	s_addc_u32 s7, s3, 0
	v_writelane_b32 v253, s6, 34
	s_cmp_eq_u32 s8, 15
	s_mov_b64 s[30:31], 0x80
	v_writelane_b32 v253, s7, 35
	s_cselect_b64 s[6:7], -1, 0
	v_writelane_b32 v253, s6, 36
	s_cmp_eq_u32 s8, 14
	s_nop 0
	v_writelane_b32 v253, s7, 37
	s_cselect_b64 s[6:7], -1, 0
	v_writelane_b32 v253, s6, 38
	s_cmp_eq_u32 s8, 13
	s_nop 0
	v_writelane_b32 v253, s7, 39
	s_cselect_b64 s[6:7], -1, 0
	v_writelane_b32 v253, s6, 40
	s_cmp_eq_u32 s8, 12
	s_nop 0
	v_writelane_b32 v253, s7, 41
	s_cselect_b64 s[6:7], -1, 0
	v_writelane_b32 v253, s6, 42
	s_cmp_eq_u32 s8, 11
	s_nop 0
	v_writelane_b32 v253, s7, 43
	s_cselect_b64 s[6:7], -1, 0
	v_writelane_b32 v253, s6, 44
	s_cmp_eq_u32 s8, 10
	s_nop 0
	v_writelane_b32 v253, s7, 45
	s_cselect_b64 s[6:7], -1, 0
	v_writelane_b32 v253, s6, 46
	s_cmp_eq_u32 s8, 9
	s_nop 0
	v_writelane_b32 v253, s7, 47
	s_cselect_b64 s[6:7], -1, 0
	v_writelane_b32 v253, s6, 48
	s_cmp_eq_u32 s8, 8
	s_nop 0
	v_writelane_b32 v253, s7, 49
	s_cselect_b64 s[6:7], -1, 0
	v_writelane_b32 v253, s6, 50
	s_cmp_eq_u32 s8, 7
	s_nop 0
	v_writelane_b32 v253, s7, 51
	s_cselect_b64 s[6:7], -1, 0
	v_writelane_b32 v253, s6, 52
	s_cmp_eq_u32 s8, 6
	s_nop 0
	v_writelane_b32 v253, s7, 53
	s_cselect_b64 s[6:7], -1, 0
	v_writelane_b32 v253, s6, 54
	s_cmp_eq_u32 s8, 5
	s_nop 0
	v_writelane_b32 v253, s7, 55
	s_cselect_b64 s[6:7], -1, 0
	v_writelane_b32 v253, s6, 56
	s_cmp_eq_u32 s8, 4
	s_nop 0
	v_writelane_b32 v253, s7, 57
	s_cselect_b64 s[6:7], -1, 0
	v_writelane_b32 v253, s6, 58
	s_cmp_eq_u32 s8, 3
	s_nop 0
	v_writelane_b32 v253, s7, 59
	s_cselect_b64 s[6:7], -1, 0
	v_writelane_b32 v253, s6, 60
	s_cmp_eq_u32 s8, 2
	s_nop 0
	v_writelane_b32 v253, s7, 61
	s_cselect_b64 s[6:7], -1, 0
	v_writelane_b32 v253, s6, 62
	s_cmp_eq_u32 s8, 1
	s_nop 0
	v_writelane_b32 v253, s7, 63
	s_cselect_b64 s[6:7], -1, 0
	v_writelane_b32 v254, s6, 0
	s_cmp_eq_u32 s8, 0
	s_nop 0
	v_writelane_b32 v254, s7, 1
	s_cselect_b64 s[6:7], -1, 0
	s_lshl_b32 s5, s9, 2
	s_add_u32 s0, s0, s5
	v_writelane_b32 v254, s6, 2
	s_addc_u32 s1, s1, 0
	s_nop 0
	v_writelane_b32 v254, s7, 3
	s_add_u32 s6, s0, 0x1400
	s_addc_u32 s7, s1, 0
	v_writelane_b32 v254, s6, 4
	s_add_u32 s0, s0, 0x2400
	s_addc_u32 s1, s1, 0
	v_writelane_b32 v254, s7, 5
	v_writelane_b32 v254, s0, 6
	s_nop 1
	v_writelane_b32 v254, s1, 7
	s_add_u32 s0, s2, 0x2dd70c00
	s_addc_u32 s1, s3, 0
	v_writelane_b32 v254, s0, 8
	s_nop 1
	v_writelane_b32 v254, s1, 9
	s_add_u32 s0, s2, 0x2dd70d00
	s_addc_u32 s1, s3, 0
	v_writelane_b32 v254, s0, 10
	s_nop 1
	v_writelane_b32 v254, s1, 11
	s_sub_i32 s0, 0, s90
	v_readfirstlane_b32 s1, v0
	s_mul_i32 s0, s0, s1
	s_mul_hi_u32 s0, s1, s0
	s_add_i32 s1, s1, s0
	s_mul_hi_u32 s0, s1, 0x1b0
	s_mul_i32 s0, s0, s90
	s_sub_i32 s0, 0x1b0, s0
	s_sub_i32 s1, s0, s90
	s_cmp_ge_u32 s0, s90
	s_cselect_b32 s0, s1, s0
	s_sub_i32 s1, s0, s90
	s_cmp_ge_u32 s0, s90
	s_cselect_b32 s0, s1, s0
	s_sub_i32 s0, s4, s0
	v_writelane_b32 v254, s0, 12
	s_lshl_b32 s0, s87, 8
	v_writelane_b32 v254, s0, 13
	s_lshl_b32 s0, s4, 8
	v_writelane_b32 v254, s0, 14
	s_lshl_b32 s0, s4, 11
	v_writelane_b32 v254, s0, 15
	s_lshl_b32 s0, s87, 11
	v_writelane_b32 v254, s0, 16
	v_writelane_b32 v254, s87, 17
	v_writelane_b32 v254, s88, 18
	s_mov_b32 s1, -2
	s_nop 0
	v_writelane_b32 v254, s89, 19
	v_writelane_b32 v254, s90, 20
	s_branch .LBB0_639

; __global__ void __launch_bounds__(NTHR, 2) mega(P p) {
;     ...
;   for (int st = -1; st < 40; st++) {
;     const int l = st < 0 ? 0 : st / 10;
;     const int ph = st < 0 ? -1 : st - l * 10;
;     const int need_ctx = l < 3;
;     const int nrows = need_ctx ? T_ALL : T_LAT;
;     switch (ph) {
.LBB0_639:
	s_and_b32 s0, s1, 0xff
	s_mulk_i32 s0, 0xcd
	s_lshr_b32 s0, s0, 11
	s_cmp_lt_i32 s1, 0
	s_cselect_b32 s94, 0, s0
	s_mul_i32 s0, s94, -10
	s_add_i32 s0, s0, s1
	s_cmp_lt_i32 s1, 0
	v_writelane_b32 v254, s1, 21
	s_cselect_b32 s2, -1, s0
	s_cmp_eq_u32 s1, -2
	s_cselect_b32 s2, 10, s2
	s_cmp_gt_u32 s94, 2
	s_mov_b32 s97, 0xc2b17218
	s_mov_b32 s96, 0x42ce8ed0
	s_cselect_b64 s[40:41], -1, 0
	s_cmp_lt_i32 s2, 4
	v_writelane_b32 v254, s2, 22
	s_cbranch_scc1 .LBB0_770
	s_and_b64 s[0:1], s[40:41], exec
	s_cselect_b32 s34, s48, 0x4800
	s_cmp_gt_i32 s2, 6
	s_cbranch_scc0 .LBB0_771
	s_cmp_gt_i32 s2, 7
	s_cbranch_scc0 .LBB0_772
	s_mov_b32 s4, s2
	s_cmp_gt_i32 s4, 8
	s_mov_b64 s[4:5], 0
	v_writelane_b32 v254, s4, 23
	s_mov_b64 s[2:3], -1
	s_mov_b64 s[0:1], 0
	v_writelane_b32 v254, s5, 24
	s_cbranch_scc0 .LBB0_644
	v_readlane_b32 s4, v254, 22
	s_cmp_lg_u32 s4, 9
	s_cselect_b64 s[4:5], -1, 0
	v_writelane_b32 v254, s4, 23
	s_mov_b64 s[2:3], 0
	s_nop 0
	v_writelane_b32 v254, s5, 24

; __global__ void __launch_bounds__(NTHR, 2) mega(P p) {
;     ...
;   grid.sync();
;   XcdBarrier xb = xcd_barrier_post((unsigned*)(p.ws + O_BAR));
.LBB0_1567:
	v_readlane_b32 s0, v254, 17
	v_readlane_b32 s2, v254, 18
	v_readlane_b32 s3, v254, 19
	s_cmp_lg_u32 s0, 0
	s_cbranch_scc1 .Lcgf_end
	s_load_dwordx2 s[4:5], s[2:3], 0x178
	v_cmp_eq_u32_e32 vcc, 0, v128
	s_and_saveexec_b64 s[6:7], vcc
	s_cbranch_execz .Lcgf_end
	v_mov_b32_e32 v0, 0
	v_mov_b32_e32 v1, 0xffff
	s_waitcnt lgkmcnt(0)
	global_atomic_add v0, v1, s[4:5] offset:32
	s_waitcnt vmcnt(0)
